# v22 + loop-edge edit in the attention softmax chain: row max as two interleaved chains, wave-uniform threshold test branches straight from the compare (no exp/select on the common path), max-update pa
# baseline (speedup 1.0000x reference)
; __device__ __forceinline__ void partialSM(f32x16& p0, f32x16& p1, float& m_reg, float& mn, float& alpha) {
;   constexpr float C = SCALE * 1.4426950408889634f;
;   float pmax = p0[0];
; #pragma unroll
;   for (int r = 1; r < 16; ++r) pmax = fmaxf(pmax, p0[r]);
; #pragma unroll
;   for (int r = 0; r < 16; ++r) pmax = fmaxf(pmax, p1[r]);
;   { auto rr = __builtin_amdgcn_permlane32_swap(__float_as_uint(pmax), __float_as_uint(pmax), false, false);
;     pmax = fmaxf(__uint_as_float(rr[0]), __uint_as_float(rr[1])); }
;   if (__builtin_expect(__all(pmax - m_reg <= THR / SCALE), 1)) { mn = m_reg; alpha = 1.f; }
;   else { mn = fmaxf(m_reg, pmax); alpha = __builtin_amdgcn_exp2f((m_reg - mn) * C); m_reg = mn; }
;   float mnC = -mn * C;
; #pragma unroll
;   for (int r = 0; r < 16; ++r) p0[r] = fmaf(p0[r], C, mnC);
; #pragma unroll
;   for (int r = 0; r < 16; ++r) p1[r] = fmaf(p1[r], C, mnC);
; #pragma unroll
;   for (int r = 0; r < 16; ++r) p0[r] = __builtin_amdgcn_exp2f(p0[r]);
; }
; __device__ __forceinline__ void finishSM(f32x16& p0, f32x16& p1, float alpha, float& l_reg, bf16x8& pa0, bf16x8& pa1, bf16x8& pa2, bf16x8& pa3) {
; #pragma unroll
;   for (int r = 0; r < 16; ++r) p1[r] = __builtin_amdgcn_exp2f(p1[r]);
;   float ps = 0;
; #pragma unroll
;   for (int r = 0; r < 16; ++r) ps += p0[r];
; #pragma unroll
;   for (int r = 0; r < 16; ++r) ps += p1[r];
;   { auto rr = __builtin_amdgcn_permlane32_swap(__float_as_uint(ps), __float_as_uint(ps), false, false);
;     ps = __uint_as_float(rr[0]) + __uint_as_float(rr[1]); }
; __device__ __forceinline__ void qkt(f32x16& p0, f32x16& p1, const char* Ks, const bf16x8* qr, int r32, int hi) {
;   p0 = f32x16{}; p1 = f32x16{};
; #pragma unroll
;   for (int d0 = 0; d0 < 8; ++d0) { int cb = (d0 * 16 + hi * 8) * 2;
;     bf16x8 b0 = *reinterpret_cast<const bf16x8*>(Ks + KSWZ(r32, cb));
;     bf16x8 b1 = *reinterpret_cast<const bf16x8*>(Ks + KSWZ(32 + r32, cb));
;     p0 = __builtin_amdgcn_mfma_f32_32x32x16_bf16(b0, qr[d0], p0, 0, 0, 0);
;     p1 = __builtin_amdgcn_mfma_f32_32x32x16_bf16(b1, qr[d0], p1, 0, 0, 0); }
.LBB0_616:
	s_and_b32 s34, s29, 1
	s_add_i32 s29, s29, 1
	s_lshl_b32 s30, s34, 14
	s_add_i32 s8, s30, 0x10010
	s_waitcnt lgkmcnt(4)
	v_mfma_f32_32x32x16_bf16 v[146:161], v[194:197], v[162:165], 0
	v_mfma_f32_32x32x16_bf16 v[130:145], v[198:201], v[162:165], 0
	v_add3_u32 v1, s8, v236, v213
	ds_read_b128 v[194:197], v1
	ds_read_b128 v[198:201], v1 offset:8192
	s_add_i32 s44, s24, -1
	s_min_u32 s44, s44, s29
	s_lshr_b32 s42, s44, 2
	s_lshl_b32 s42, s42, 19
	s_and_b32 s43, s44, 3
	s_lshl_b32 s43, s43, 15
	s_add_u32 s44, s42, s43
	s_add_u32 s42, s10, s44
	s_addc_u32 s43, s11, 0
	s_add_u32 s100, s12, s44
	s_addc_u32 s101, s13, 0
	s_xor_b32 s39, s30, 0x4000
	s_add_i32 s39, s27, s39
	s_lshl_b32 s9, s34, 15
	s_xor_b32 s9, s9, 0x8000
	s_add_i32 s9, s28, s9
	v_lshl_add_u32 v251, s34, 15, v242
	s_mov_b32 m0, s39
	s_waitcnt lgkmcnt(4)
	v_mfma_f32_32x32x16_bf16 v[146:161], v[202:205], v[166:169], v[146:161]
	v_mfma_f32_32x32x16_bf16 v[130:145], v[206:209], v[166:169], v[130:145]
	global_load_lds_dwordx4 v214, s[42:43]
	v_add3_u32 v1, s8, v238, v213
	ds_read_b128 v[202:205], v1
	ds_read_b128 v[206:209], v1 offset:8192
	s_add_i32 m0, s39, 0x400
	s_waitcnt lgkmcnt(4)
	v_mfma_f32_32x32x16_bf16 v[146:161], v[246:249], v[170:173], v[146:161]
	v_mfma_f32_32x32x16_bf16 v[130:145], v[252:255], v[170:173], v[130:145]
	global_load_lds_dwordx4 v215, s[42:43]
	v_add3_u32 v1, s8, v239, v213
	ds_read_b128 v[246:249], v1
	ds_read_b128 v[252:255], v1 offset:8192
	s_mov_b32 m0, s9
	s_waitcnt lgkmcnt(4)
	v_mfma_f32_32x32x16_bf16 v[146:161], v[194:197], v[174:177], v[146:161]
	v_mfma_f32_32x32x16_bf16 v[130:145], v[198:201], v[174:177], v[130:145]
	global_load_lds_dwordx4 v216, s[100:101]
	v_add3_u32 v1, s8, v240, v213
	ds_read_b128 v[194:197], v1
	ds_read_b128 v[198:201], v1 offset:8192
	s_add_i32 m0, s9, 0x400
	s_waitcnt lgkmcnt(4)
	v_mfma_f32_32x32x16_bf16 v[146:161], v[202:205], v[178:181], v[146:161]
	v_mfma_f32_32x32x16_bf16 v[130:145], v[206:209], v[178:181], v[130:145]
	global_load_lds_dwordx4 v217, s[100:101]
	v_add3_u32 v1, s8, v241, v213
	ds_read_b128 v[202:205], v1
	ds_read_b128 v[206:209], v1 offset:8192
	s_add_i32 m0, s9, 0x800
	s_waitcnt lgkmcnt(4)
	v_mfma_f32_32x32x16_bf16 v[146:161], v[246:249], v[182:185], v[146:161]
	v_mfma_f32_32x32x16_bf16 v[130:145], v[252:255], v[182:185], v[130:145]
	global_load_lds_dwordx4 v218, s[100:101]
	s_add_i32 m0, s9, 0xc00
	ds_read_b64_tr_b16 v[246:247], v251 offset:0
	ds_read_b64_tr_b16 v[248:249], v251 offset:4096
	ds_read_b64_tr_b16 v[252:253], v251 offset:8192
	ds_read_b64_tr_b16 v[254:255], v251 offset:12288
	s_waitcnt lgkmcnt(6)
	v_mfma_f32_32x32x16_bf16 v[146:161], v[194:197], v[186:189], v[146:161]
	v_mfma_f32_32x32x16_bf16 v[130:145], v[198:201], v[186:189], v[130:145]
	global_load_lds_dwordx4 v219, s[100:101]
	s_mov_b32 s8, 0x42b504f3
	s_waitcnt lgkmcnt(4)
	v_mfma_f32_32x32x16_bf16 v[146:161], v[202:205], v[190:193], v[146:161]
	v_mfma_f32_32x32x16_bf16 v[130:145], v[206:209], v[190:193], v[130:145]
	s_nop 10
	v_max3_f32 v1, v146, v147, v148
	v_max3_f32 v1, v1, v149, v150
	v_max3_f32 v194, v130, v131, v132
	v_max3_f32 v1, v1, v151, v152
	v_max3_f32 v194, v194, v133, v134
	v_max3_f32 v1, v1, v153, v154
	v_max3_f32 v194, v194, v135, v136
	v_max3_f32 v1, v1, v155, v156
	v_max3_f32 v194, v194, v137, v138
	v_max3_f32 v1, v1, v157, v158
	v_max3_f32 v194, v194, v139, v140
	v_max3_f32 v1, v1, v159, v160
	v_max3_f32 v194, v194, v141, v142
	v_max_f32_e32 v1, v1, v161
	v_max3_f32 v194, v194, v143, v144
	v_max_f32_e32 v194, v194, v145
	v_max_f32_e32 v1, v1, v194
	v_mov_b32_e32 v194, v1
	s_nop 1
	v_permlane32_swap_b32_e32 v1, v194
	v_max_f32_e32 v1, v1, v194
	v_sub_f32_e32 v194, v1, v243
	v_cmp_ge_f32_e32 vcc, s8, v194
	s_cmp_eq_u64 vcc, exec
	s_cbranch_scc0 .Lsm_slow
	v_mov_b32_e32 v1, 1.0
.LBB0_624:
	v_mul_f32_e32 v194, 0xbe0293ee, v243
	v_fmamk_f32 v146, v146, 0x3e0293ee, v194
	v_fmamk_f32 v147, v147, 0x3e0293ee, v194
	v_fmamk_f32 v148, v148, 0x3e0293ee, v194
	v_fmamk_f32 v149, v149, 0x3e0293ee, v194
	v_fmamk_f32 v150, v150, 0x3e0293ee, v194
	v_fmamk_f32 v151, v151, 0x3e0293ee, v194
	v_fmamk_f32 v152, v152, 0x3e0293ee, v194
	v_fmamk_f32 v153, v153, 0x3e0293ee, v194
	v_fmamk_f32 v154, v154, 0x3e0293ee, v194
	v_fmamk_f32 v155, v155, 0x3e0293ee, v194
	v_fmamk_f32 v156, v156, 0x3e0293ee, v194
	v_fmamk_f32 v157, v157, 0x3e0293ee, v194
	v_fmamk_f32 v158, v158, 0x3e0293ee, v194
	v_fmamk_f32 v159, v159, 0x3e0293ee, v194
	v_fmamk_f32 v160, v160, 0x3e0293ee, v194
	v_fmamk_f32 v161, v161, 0x3e0293ee, v194
	v_fmamk_f32 v130, v130, 0x3e0293ee, v194
	v_fmamk_f32 v131, v131, 0x3e0293ee, v194
	v_fmamk_f32 v132, v132, 0x3e0293ee, v194
	v_fmamk_f32 v133, v133, 0x3e0293ee, v194
	v_fmamk_f32 v134, v134, 0x3e0293ee, v194
	v_fmamk_f32 v135, v135, 0x3e0293ee, v194
	v_fmamk_f32 v136, v136, 0x3e0293ee, v194
	v_fmamk_f32 v137, v137, 0x3e0293ee, v194
	v_fmamk_f32 v138, v138, 0x3e0293ee, v194
	v_fmamk_f32 v139, v139, 0x3e0293ee, v194
	v_fmamk_f32 v140, v140, 0x3e0293ee, v194
	v_fmamk_f32 v141, v141, 0x3e0293ee, v194
	v_fmamk_f32 v142, v142, 0x3e0293ee, v194
	v_fmamk_f32 v143, v143, 0x3e0293ee, v194
	v_fmamk_f32 v144, v144, 0x3e0293ee, v194
	v_fmac_f32_e32 v194, 0x3e0293ee, v145
	v_exp_f32_e32 v145, v146
	v_exp_f32_e32 v147, v147
	v_exp_f32_e32 v148, v148
	v_exp_f32_e32 v149, v149
	v_exp_f32_e32 v150, v150
	v_exp_f32_e32 v195, v130
	v_add_f32_e32 v130, 0, v145
	v_exp_f32_e32 v151, v151
	v_add_f32_e32 v130, v147, v130
	v_exp_f32_e32 v152, v152
	v_add_f32_e32 v130, v148, v130
	v_exp_f32_e32 v153, v153
	v_add_f32_e32 v130, v149, v130
	v_exp_f32_e32 v154, v154
	v_add_f32_e32 v130, v150, v130
	v_exp_f32_e32 v155, v155
	v_add_f32_e32 v130, v151, v130
; #define SBAR() __builtin_amdgcn_sched_barrier(0)
; #define STEP(D, CUR, NXT) v_load<D + 1>(NXT, vb); asm volatile("s_waitcnt lgkmcnt(8)" ::: "memory"); SBAR(); pv_mma(o[D], CUR, pa0, pa1, pa2, pa3); SBAR();
; __device__ __forceinline__ void finishSM(f32x16& p0, f32x16& p1, float alpha, float& l_reg, bf16x8& pa0, bf16x8& pa1, bf16x8& pa2, bf16x8& pa3) {
; #pragma unroll
;   for (int r = 0; r < 16; ++r) p1[r] = __builtin_amdgcn_exp2f(p1[r]);
;   float ps = 0;
; #pragma unroll
;   for (int r = 0; r < 16; ++r) ps += p0[r];
; #pragma unroll
;   for (int r = 0; r < 16; ++r) ps += p1[r];
;   { auto rr = __builtin_amdgcn_permlane32_swap(__float_as_uint(ps), __float_as_uint(ps), false, false);
;     ps = __uint_as_float(rr[0]) + __uint_as_float(rr[1]); }
;   l_reg = l_reg * alpha + ps;
;     ...
;   PK4(p0, 0, pa0); PK4(p0, 8, pa1); PK4(p1, 0, pa2); PK4(p1, 8, pa3);
; template <int D0> __device__ __forceinline__ void v_load(VFrag& f, int vb) {
;   f.l0 = tr_read<v_rd_off(D0, 0, 0)>(vb); f.h0 = tr_read<v_rd_off(D0, 0, 1)>(vb); f.l1 = tr_read<v_rd_off(D0, 1, 0)>(vb); f.h1 = tr_read<v_rd_off(D0, 1, 1)>(vb);
;   f.l2 = tr_read<v_rd_off(D0, 2, 0)>(vb); f.h2 = tr_read<v_rd_off(D0, 2, 1)>(vb); f.l3 = tr_read<v_rd_off(D0, 3, 0)>(vb); f.h3 = tr_read<v_rd_off(D0, 3, 1)>(vb);
; }
; __device__ __forceinline__ void pv_mma(f32x16& od, const VFrag& f, bf16x8 pa0, bf16x8 pa1, bf16x8 pa2, bf16x8 pa3) {
;     ...
;   od = __builtin_amdgcn_mfma_f32_32x32x16_bf16(pa0, PK(f.l0, f.h0), od, 0, 0, 0);
;   od = __builtin_amdgcn_mfma_f32_32x32x16_bf16(pa1, PK(f.l1, f.h1), od, 0, 0, 0);
;   od = __builtin_amdgcn_mfma_f32_32x32x16_bf16(pa2, PK(f.l2, f.h2), od, 0, 0, 0);
;   od = __builtin_amdgcn_mfma_f32_32x32x16_bf16(pa3, PK(f.l3, f.h3), od, 0, 0, 0);
;     ...
; }
; __device__ __forceinline__ void pv_all(f32x16* o, int vb, bf16x8 pa0, bf16x8 pa1, bf16x8 pa2, bf16x8 pa3) {
;   VFrag fa, fb;
;   v_load<0>(fa, vb);
;     ...
;   STEP(0, fa, fb) STEP(1, fb, fa) STEP(2, fa, fb) STEP(3, fb, fa) STEP(4, fa, fb) STEP(5, fb, fa) STEP(6, fa, fb)
;     ...
;   asm volatile("s_waitcnt lgkmcnt(0)" ::: "memory"); SBAR(); pv_mma(o[7], fb, pa0, pa1, pa2, pa3);
; }
	v_exp_f32_e32 v156, v156
	v_add_f32_e32 v130, v152, v130
	v_exp_f32_e32 v157, v157
	v_add_f32_e32 v130, v153, v130
	v_exp_f32_e32 v158, v158
	v_add_f32_e32 v130, v154, v130
	v_exp_f32_e32 v159, v159
	v_add_f32_e32 v130, v155, v130
	v_exp_f32_e32 v160, v160
	v_add_f32_e32 v130, v156, v130
	v_exp_f32_e32 v161, v161
	v_add_f32_e32 v130, v157, v130
	v_add_f32_e32 v130, v158, v130
	v_exp_f32_e32 v196, v131
	v_add_f32_e32 v130, v159, v130
	v_exp_f32_e32 v197, v132
	v_add_f32_e32 v130, v160, v130
	v_exp_f32_e32 v198, v133
	v_add_f32_e32 v130, v161, v130
	v_exp_f32_e32 v199, v134
	v_add_f32_e32 v130, v195, v130
	v_exp_f32_e32 v200, v135
	v_add_f32_e32 v130, v196, v130
	v_exp_f32_e32 v201, v136
	v_add_f32_e32 v130, v197, v130
	v_exp_f32_e32 v202, v137
	v_add_f32_e32 v130, v198, v130
	v_exp_f32_e32 v203, v138
	v_add_f32_e32 v130, v199, v130
	v_exp_f32_e32 v204, v139
	v_add_f32_e32 v130, v200, v130
	v_exp_f32_e32 v205, v140
	v_add_f32_e32 v130, v201, v130
	v_exp_f32_e32 v206, v141
	v_add_f32_e32 v130, v202, v130
	v_exp_f32_e32 v207, v142
	v_add_f32_e32 v130, v203, v130
	v_exp_f32_e32 v208, v143
	v_add_f32_e32 v130, v204, v130
	v_exp_f32_e32 v209, v144
	v_add_f32_e32 v130, v205, v130
	v_exp_f32_e32 v194, v194
	v_add_f32_e32 v130, v206, v130
	v_add_f32_e32 v130, v207, v130
	v_add_f32_e32 v130, v208, v130
	v_add_f32_e32 v130, v209, v130
	v_add_f32_e32 v130, v194, v130
	v_mov_b32_e32 v131, v130
	s_nop 1
	v_permlane32_swap_b32_e32 v130, v131
	v_add_f32_e32 v146, v130, v131
	v_fmac_f32_e32 v146, v244, v1
	v_cvt_pk_bf16_f32 v130, v145, v147
	v_cvt_pk_bf16_f32 v131, v148, v149
	v_cvt_pk_bf16_f32 v132, v150, v151
	v_cvt_pk_bf16_f32 v133, v152, v153
	v_cvt_pk_bf16_f32 v134, v154, v155
	v_cvt_pk_bf16_f32 v135, v156, v157
	v_cvt_pk_bf16_f32 v136, v158, v159
	v_cvt_pk_bf16_f32 v137, v160, v161
	v_cvt_pk_bf16_f32 v138, v195, v196
	v_cvt_pk_bf16_f32 v139, v197, v198
	v_cvt_pk_bf16_f32 v140, v199, v200
	v_cvt_pk_bf16_f32 v141, v201, v202
	v_cvt_pk_bf16_f32 v142, v203, v204
	v_cvt_pk_bf16_f32 v143, v205, v206
	v_cvt_pk_bf16_f32 v144, v207, v208
	v_cvt_pk_bf16_f32 v145, v209, v194
	s_nop 0
	v_permlane32_swap_b32_e32 v130, v132
	v_permlane32_swap_b32_e32 v131, v133
	v_permlane32_swap_b32_e32 v134, v136
	v_permlane32_swap_b32_e32 v135, v137
	v_permlane32_swap_b32_e32 v138, v140
	v_permlane32_swap_b32_e32 v139, v141
	v_permlane32_swap_b32_e32 v142, v144
	v_permlane32_swap_b32_e32 v143, v145
	ds_read_b64_tr_b16 v[156:157], v251 offset:512
	ds_read_b64_tr_b16 v[158:159], v251 offset:4608
	ds_read_b64_tr_b16 v[194:195], v251 offset:8704
	ds_read_b64_tr_b16 v[196:197], v251 offset:12800
	ds_read_b64_tr_b16 v[198:199], v251 offset:1024
	ds_read_b64_tr_b16 v[200:201], v251 offset:5120
	ds_read_b64_tr_b16 v[202:203], v251 offset:9216
	ds_read_b64_tr_b16 v[204:205], v251 offset:13312
	s_waitcnt lgkmcnt(8)
	v_mfma_f32_32x32x16_bf16 v[114:129], v[130:133], v[246:249], v[114:129]
	ds_read_b64_tr_b16 v[148:149], v251 offset:1536
	ds_read_b64_tr_b16 v[150:151], v251 offset:5632
	ds_read_b64_tr_b16 v[152:153], v251 offset:9728
	ds_read_b64_tr_b16 v[154:155], v251 offset:13824
	v_mfma_f32_32x32x16_bf16 v[114:129], v[134:137], v[252:255], v[114:129]
	s_waitcnt lgkmcnt(8)
	v_mfma_f32_32x32x16_bf16 v[98:113], v[130:133], v[156:159], v[98:113]
	ds_read_b64_tr_b16 v[206:207], v251 offset:2048
	ds_read_b64_tr_b16 v[208:209], v251 offset:6144
	ds_read_b64_tr_b16 v[244:245], v251 offset:10240
	ds_read_b64_tr_b16 v[246:247], v251 offset:14336
	v_mfma_f32_32x32x16_bf16 v[98:113], v[134:137], v[194:197], v[98:113]
	s_waitcnt lgkmcnt(8)
	v_mfma_f32_32x32x16_bf16 v[82:97], v[130:133], v[198:201], v[82:97]
	ds_read_b64_tr_b16 v[156:157], v251 offset:2560
	ds_read_b64_tr_b16 v[158:159], v251 offset:6656
	ds_read_b64_tr_b16 v[194:195], v251 offset:10752
	ds_read_b64_tr_b16 v[196:197], v251 offset:14848
	v_mfma_f32_32x32x16_bf16 v[82:97], v[134:137], v[202:205], v[82:97]
	s_waitcnt lgkmcnt(8)
	v_mfma_f32_32x32x16_bf16 v[66:81], v[130:133], v[148:151], v[66:81]
	ds_read_b64_tr_b16 v[198:199], v251 offset:3072
	ds_read_b64_tr_b16 v[200:201], v251 offset:7168
	ds_read_b64_tr_b16 v[202:203], v251 offset:11264
	ds_read_b64_tr_b16 v[204:205], v251 offset:15360
	v_mfma_f32_32x32x16_bf16 v[66:81], v[134:137], v[152:155], v[66:81]
	s_waitcnt lgkmcnt(8)
	v_mfma_f32_32x32x16_bf16 v[50:65], v[130:133], v[206:209], v[50:65]
	ds_read_b64_tr_b16 v[148:149], v251 offset:3584
	ds_read_b64_tr_b16 v[150:151], v251 offset:7680
	ds_read_b64_tr_b16 v[152:153], v251 offset:11776
	ds_read_b64_tr_b16 v[154:155], v251 offset:15872
	v_mfma_f32_32x32x16_bf16 v[50:65], v[134:137], v[244:247], v[50:65]
	s_waitcnt lgkmcnt(8)
	v_mfma_f32_32x32x16_bf16 v[34:49], v[130:133], v[156:159], v[34:49]
	ds_read_b64_tr_b16 v[206:207], v251 offset:16384
	ds_read_b64_tr_b16 v[208:209], v251 offset:20480
	ds_read_b64_tr_b16 v[244:245], v251 offset:24576
	ds_read_b64_tr_b16 v[246:247], v251 offset:28672
	v_mfma_f32_32x32x16_bf16 v[34:49], v[134:137], v[194:197], v[34:49]
	s_waitcnt lgkmcnt(8)
	v_mfma_f32_32x32x16_bf16 v[18:33], v[130:133], v[198:201], v[18:33]
	ds_read_b64_tr_b16 v[156:157], v251 offset:16896
	ds_read_b64_tr_b16 v[158:159], v251 offset:20992
	ds_read_b64_tr_b16 v[194:195], v251 offset:25088
	ds_read_b64_tr_b16 v[196:197], v251 offset:29184
	v_mfma_f32_32x32x16_bf16 v[18:33], v[134:137], v[202:205], v[18:33]
	s_waitcnt lgkmcnt(8)
	v_mfma_f32_32x32x16_bf16 v[2:17], v[130:133], v[148:151], v[2:17]
	ds_read_b64_tr_b16 v[198:199], v251 offset:17408
	ds_read_b64_tr_b16 v[200:201], v251 offset:21504
	ds_read_b64_tr_b16 v[202:203], v251 offset:25600
	ds_read_b64_tr_b16 v[204:205], v251 offset:29696
	v_mfma_f32_32x32x16_bf16 v[2:17], v[134:137], v[152:155], v[2:17]
	s_waitcnt lgkmcnt(8)
; #define SBAR() __builtin_amdgcn_sched_barrier(0)
; __device__ __forceinline__ int crow(int r, int hi) { return (r & 3) + 8 * (r >> 2) + 4 * hi; }
; #define STEP(D, CUR, NXT) v_load<D + 1>(NXT, vb); asm volatile("s_waitcnt lgkmcnt(8)" ::: "memory"); SBAR(); pv_mma(o[D], CUR, pa0, pa1, pa2, pa3); SBAR();
; __device__ __forceinline__ void pv_all(f32x16* o, int vb, bf16x8 pa0, bf16x8 pa1, bf16x8 pa2, bf16x8 pa3) {
;   VFrag fa, fb;
;   v_load<0>(fa, vb);
;     ...
;   STEP(0, fa, fb) STEP(1, fb, fa) STEP(2, fa, fb) STEP(3, fb, fa) STEP(4, fa, fb) STEP(5, fb, fa) STEP(6, fa, fb)
;     ...
;   asm volatile("s_waitcnt lgkmcnt(0)" ::: "memory"); SBAR(); pv_mma(o[7], fb, pa0, pa1, pa2, pa3);
; }
; __device__ __forceinline__ void body(const bf16_t* __restrict__ Qb, const bf16_t* __restrict__ Kh, const bf16_t* __restrict__ Vh, bf16_t* __restrict__ Ob, int seq, char* lds) {
;     ...
;   for (int j = 0; j < NT; ++j) {
;     const int b = j & 1;
;     f32x16 p0, p1; float mn, al; bf16x8 pa0, pa1, pa2, pa3;
;     if (j + 1 < NT) STAGE(b ^ 1, (j + 1) * KVBLK);
;     SBAR(); qkt(p0, p1, K_lds + b * SK, qr, r32, hi);
;     partialSM(p0, p1, m_reg, mn, al);
;     if (__any(al < 1.f)) { if (hi == 0) al_l[r32] = al; asm volatile("s_waitcnt lgkmcnt(0)" ::: "memory");
; #pragma unroll
;       for (int d = 0; d < 8; ++d)
; #pragma unroll
;         for (int r = 0; r < 16; ++r) o[d][r] *= al_l[crow(r, hi)]; }
;     finishSM(p0, p1, al, l_reg, pa0, pa1, pa2, pa3); SBAR();
;     const int vb = vb0 + b * SV;
;     pv_all(o, vb, pa0, pa1, pa2, pa3);
;     asm volatile("s_waitcnt vmcnt(0) lgkmcnt(0)" ::: "memory"); __builtin_amdgcn_s_barrier(); asm volatile("" ::: "memory");
;   }
	v_mfma_f32_32x32x16_bf16 v[114:129], v[138:141], v[206:209], v[114:129]
	ds_read_b64_tr_b16 v[148:149], v251 offset:17920
	ds_read_b64_tr_b16 v[150:151], v251 offset:22016
	ds_read_b64_tr_b16 v[152:153], v251 offset:26112
	ds_read_b64_tr_b16 v[154:155], v251 offset:30208
	v_mfma_f32_32x32x16_bf16 v[114:129], v[142:145], v[244:247], v[114:129]
	s_waitcnt lgkmcnt(8)
	v_mfma_f32_32x32x16_bf16 v[98:113], v[138:141], v[156:159], v[98:113]
	ds_read_b64_tr_b16 v[206:207], v251 offset:18432
	ds_read_b64_tr_b16 v[208:209], v251 offset:22528
	ds_read_b64_tr_b16 v[244:245], v251 offset:26624
	ds_read_b64_tr_b16 v[246:247], v251 offset:30720
	v_mfma_f32_32x32x16_bf16 v[98:113], v[142:145], v[194:197], v[98:113]
	s_waitcnt lgkmcnt(8)
	v_mfma_f32_32x32x16_bf16 v[82:97], v[138:141], v[198:201], v[82:97]
	ds_read_b64_tr_b16 v[156:157], v251 offset:18944
	ds_read_b64_tr_b16 v[158:159], v251 offset:23040
	ds_read_b64_tr_b16 v[194:195], v251 offset:27136
	ds_read_b64_tr_b16 v[196:197], v251 offset:31232
	v_mfma_f32_32x32x16_bf16 v[82:97], v[142:145], v[202:205], v[82:97]
	s_waitcnt lgkmcnt(8)
	v_mfma_f32_32x32x16_bf16 v[66:81], v[138:141], v[148:151], v[66:81]
	ds_read_b64_tr_b16 v[198:199], v251 offset:19456
	ds_read_b64_tr_b16 v[200:201], v251 offset:23552
	ds_read_b64_tr_b16 v[202:203], v251 offset:27648
	ds_read_b64_tr_b16 v[204:205], v251 offset:31744
	v_mfma_f32_32x32x16_bf16 v[66:81], v[142:145], v[152:155], v[66:81]
	s_waitcnt lgkmcnt(8)
	v_mfma_f32_32x32x16_bf16 v[50:65], v[138:141], v[206:209], v[50:65]
	ds_read_b64_tr_b16 v[148:149], v251 offset:19968
	ds_read_b64_tr_b16 v[150:151], v251 offset:24064
	ds_read_b64_tr_b16 v[152:153], v251 offset:28160
	ds_read_b64_tr_b16 v[154:155], v251 offset:32256
	v_mfma_f32_32x32x16_bf16 v[50:65], v[142:145], v[244:247], v[50:65]
	s_waitcnt lgkmcnt(8)
	v_mfma_f32_32x32x16_bf16 v[34:49], v[138:141], v[156:159], v[34:49]
	v_mfma_f32_32x32x16_bf16 v[34:49], v[142:145], v[194:197], v[34:49]
	s_waitcnt lgkmcnt(4)
	v_mfma_f32_32x32x16_bf16 v[18:33], v[138:141], v[198:201], v[18:33]
	v_mfma_f32_32x32x16_bf16 v[18:33], v[142:145], v[202:205], v[18:33]
	s_waitcnt vmcnt(0) lgkmcnt(0)
	s_barrier
	s_and_b32 s8, s29, 1
	s_lshl_b32 s8, s8, 14
	s_add_i32 s8, s8, 0x10010
	v_add3_u32 v1, s8, v233, v213
	ds_read_b128 v[194:197], v1
	ds_read_b128 v[198:201], v1 offset:8192
	v_add3_u32 v1, s8, v234, v213
	ds_read_b128 v[202:205], v1
	ds_read_b128 v[206:209], v1 offset:8192
	v_add3_u32 v1, s8, v235, v213
	ds_read_b128 v[246:249], v1
	ds_read_b128 v[252:255], v1 offset:8192
	s_cmp_eq_u32 s24, s29
	v_mfma_f32_32x32x16_bf16 v[2:17], v[138:141], v[148:151], v[2:17]
	v_mfma_f32_32x32x16_bf16 v[2:17], v[142:145], v[152:155], v[2:17]
	s_cbranch_scc1 .LBB0_626
	v_mov_b32_e32 v244, v146
	s_branch .LBB0_616
.Lsm_slow:
	v_max_f32_e32 v194, v243, v243
	v_max_f32_e32 v245, v194, v1
	v_sub_f32_e32 v1, v243, v245
	v_mul_f32_e32 v1, 0x3e0293ee, v1
	v_exp_f32_e32 v1, v1
	v_mov_b32_e32 v243, v245
	v_cmp_gt_f32_e32 vcc, 1.0, v1
	s_cbranch_vccz .LBB0_624
	s_and_saveexec_b64 s[54:55], s[6:7]
	ds_write_b32 v237, v1 offset:128
	s_or_b64 exec, exec, s[54:55]
	s_waitcnt lgkmcnt(0)
	v_add_u32_e32 v194, v211, v212
	ds_read_b128 v[206:209], v194 offset:224
	ds_read_b128 v[202:205], v194 offset:192
	ds_read_b128 v[198:201], v194 offset:160
	ds_read_b128 v[194:197], v194 offset:128
	s_waitcnt lgkmcnt(0)
	v_pk_mul_f32 v[126:127], v[126:127], v[206:207]
	v_pk_mul_f32 v[122:123], v[122:123], v[202:203]
	v_pk_mul_f32 v[118:119], v[118:119], v[198:199]
	v_pk_mul_f32 v[128:129], v[128:129], v[208:209]
	v_pk_mul_f32 v[124:125], v[124:125], v[204:205]
	v_pk_mul_f32 v[120:121], v[120:121], v[200:201]
	v_pk_mul_f32 v[116:117], v[116:117], v[196:197]
	v_pk_mul_f32 v[114:115], v[114:115], v[194:195]
	v_pk_mul_f32 v[110:111], v[110:111], v[206:207]
	v_pk_mul_f32 v[106:107], v[106:107], v[202:203]
	v_pk_mul_f32 v[102:103], v[102:103], v[198:199]
	v_pk_mul_f32 v[112:113], v[112:113], v[208:209]
	v_pk_mul_f32 v[108:109], v[108:109], v[204:205]
	v_pk_mul_f32 v[104:105], v[104:105], v[200:201]
	v_pk_mul_f32 v[100:101], v[100:101], v[196:197]
	v_pk_mul_f32 v[98:99], v[98:99], v[194:195]
	v_pk_mul_f32 v[94:95], v[94:95], v[206:207]
	v_pk_mul_f32 v[90:91], v[90:91], v[202:203]
	v_pk_mul_f32 v[86:87], v[86:87], v[198:199]
	v_pk_mul_f32 v[96:97], v[96:97], v[208:209]
	v_pk_mul_f32 v[92:93], v[92:93], v[204:205]
	v_pk_mul_f32 v[88:89], v[88:89], v[200:201]
	v_pk_mul_f32 v[84:85], v[84:85], v[196:197]
	v_pk_mul_f32 v[82:83], v[82:83], v[194:195]
	v_pk_mul_f32 v[78:79], v[78:79], v[206:207]
	v_pk_mul_f32 v[74:75], v[74:75], v[202:203]
	v_pk_mul_f32 v[70:71], v[70:71], v[198:199]
	v_pk_mul_f32 v[80:81], v[80:81], v[208:209]
	v_pk_mul_f32 v[76:77], v[76:77], v[204:205]
	v_pk_mul_f32 v[72:73], v[72:73], v[200:201]
	v_pk_mul_f32 v[68:69], v[68:69], v[196:197]
	v_pk_mul_f32 v[66:67], v[66:67], v[194:195]
	v_pk_mul_f32 v[62:63], v[62:63], v[206:207]
	v_pk_mul_f32 v[58:59], v[58:59], v[202:203]
	v_pk_mul_f32 v[54:55], v[54:55], v[198:199]
	v_pk_mul_f32 v[64:65], v[64:65], v[208:209]
	v_pk_mul_f32 v[60:61], v[60:61], v[204:205]
	v_pk_mul_f32 v[56:57], v[56:57], v[200:201]
	v_pk_mul_f32 v[52:53], v[52:53], v[196:197]
	v_pk_mul_f32 v[50:51], v[50:51], v[194:195]
	v_pk_mul_f32 v[46:47], v[46:47], v[206:207]
	v_pk_mul_f32 v[42:43], v[42:43], v[202:203]
	v_pk_mul_f32 v[38:39], v[38:39], v[198:199]
	v_pk_mul_f32 v[48:49], v[48:49], v[208:209]
	v_pk_mul_f32 v[44:45], v[44:45], v[204:205]
	v_pk_mul_f32 v[40:41], v[40:41], v[200:201]
	v_pk_mul_f32 v[36:37], v[36:37], v[196:197]
	v_pk_mul_f32 v[34:35], v[34:35], v[194:195]
	v_pk_mul_f32 v[30:31], v[30:31], v[206:207]
	v_pk_mul_f32 v[26:27], v[26:27], v[202:203]
	v_pk_mul_f32 v[22:23], v[22:23], v[198:199]
	v_pk_mul_f32 v[32:33], v[32:33], v[208:209]
	v_pk_mul_f32 v[28:29], v[28:29], v[204:205]
	v_pk_mul_f32 v[24:25], v[24:25], v[200:201]
	v_pk_mul_f32 v[20:21], v[20:21], v[196:197]
	v_pk_mul_f32 v[18:19], v[18:19], v[194:195]
	v_pk_mul_f32 v[14:15], v[14:15], v[206:207]
	v_pk_mul_f32 v[10:11], v[10:11], v[202:203]
	v_pk_mul_f32 v[6:7], v[6:7], v[198:199]
	v_pk_mul_f32 v[16:17], v[16:17], v[208:209]
	v_pk_mul_f32 v[12:13], v[12:13], v[204:205]
	v_pk_mul_f32 v[8:9], v[8:9], v[200:201]
	v_pk_mul_f32 v[4:5], v[4:5], v[196:197]
	v_pk_mul_f32 v[2:3], v[2:3], v[194:195]
	s_branch .LBB0_624
